# attention units: wave 0 computes the next unit's KV-window start during the epilogue and publishes it through LDS (removes one dependent load round trip per unit)
# baseline (speedup 1.0000x reference)
; template<int THRL> __device__ __forceinline__ void attn_unit(int b,int h,int qb,int t0,float cqv,float mfix,const float*__restrict__ cf,float cref,unsigned*counter,const bf16*Q,const bf16*__restrict__ K,const bf16*__restrict__ V,bf16*O,const bf16*__restrict__ G,char*shm){
;     ...
;   for(int d0=0;d0<4;++d0)qr[d0]=*reinterpret_cast<const bf16x8*>(&Qw[(long)r32*DM+d0*16+hi*8]);
; template<int THRL> __device__ __forceinline__ void fox_attn_phase(char*lds,const bf16*Q,const bf16*K,const bf16*V,bf16*O,const bf16*G,const float*__restrict__ cumf,unsigned*counter,float TH,float mfix){
;     ...
;   for(;;){
;     const int u=shi[0];
;     if(u>=NQB*BATCH*NHEAD) break;
;     const int qb=NQB-1-(u&31), bh=sorted[u>>5], q0=qb*QB;
;     const float* cf=cumf+(long)bh*SEQ;
;     const float cref=cf[q0];
;     const int nb=4*qb; float e0=0.f,e1=0.f;
;     if(lane<nb) e0=cf[64*lane+63];
;     if(lane+64<nb) e1=cf[64*(lane+64)+63];
;     const float cqr=cf[q0+wid*QBLK+(lane&31)];
.LBB0_842:
	s_add_i32 s60, 0, 0x1c800
	s_waitcnt lgkmcnt(14)
	v_mov_b32_e32 v2, s60
	s_waitcnt lgkmcnt(0)
	s_barrier
	ds_read_b32 v2, v2
	s_movk_i32 s4, 0x3ff
	s_mov_b32 s41, 0
	s_waitcnt lgkmcnt(0)
	v_cmp_lt_i32_e32 vcc, s4, v2
	v_readfirstlane_b32 s4, v2
	s_cbranch_vccnz .LBB0_922
	s_add_u32 s61, s10, 0x5800000
	s_addc_u32 s0, s11, 0
	s_add_u32 s1, s10, 0x7800000
	v_mul_f32_e32 v0, 0x41000000, v0
	s_addc_u32 s64, s11, 0
	v_mul_f32_e32 v0, v1, v0
	v_and_b32_e32 v2, 31, v216
	v_mul_f32_e32 v0, 0x3f8147ae, v0
	v_mov_b32_e32 v205, 0
	s_add_u32 s42, s10, 0x1701800
	s_mov_b32 s50, 0xfffe0000
	v_mul_f32_e32 v222, 0x3fb8aa3b, v0
	v_lshl_or_b32 v202, s16, 5, v2
	v_mov_b32_e32 v203, v205
	s_addc_u32 s43, s11, 0
	s_mov_b64 s[44:45], 0x20000
	s_mov_b64 s[46:47], 0x40000
	s_mov_b64 s[48:49], 0x60000
	s_mov_b32 s51, -1
	v_mov_b32_e32 v223, 0xff800000
	s_mov_b32 s32, -1
	s_branch .LBB0_845
.LBB0_844:
	s_or_b64 exec, exec, s[4:5]
	s_waitcnt lgkmcnt(0)
	s_barrier
	v_mov_b32_e32 v0, s60
	ds_read_b32 v0, v0
	v_mov_b32_e32 v250, s60
	ds_read_b32 v250, v250 offset:4
	s_movk_i32 s4, 0x400
	s_waitcnt lgkmcnt(0)
	v_readfirstlane_b32 s32, v250
	v_cmp_gt_i32_e32 vcc, s4, v0
	v_readfirstlane_b32 s4, v0
	s_cbranch_vccz .LBB0_921
.LBB0_845:
	s_andn2_b32 s17, 31, s4
	s_ashr_i32 s4, s4, 5
	s_lshl_b32 s4, s4, 2
	s_add_i32 s4, s4, 0
	s_add_i32 s4, s4, 0x1c8c0
	v_mov_b32_e32 v0, s4
	ds_read_b32 v0, v0
	s_lshl_b32 s40, s17, 10
	v_mov_b32_e32 v4, s40
	s_lshl_b32 s70, s17, 2
	v_cmp_le_u32_e32 vcc, s70, v217
	s_waitcnt lgkmcnt(0)
	v_ashrrev_i32_e32 v1, 31, v0
	v_readfirstlane_b32 s16, v0
	v_lshlrev_b64 v[0:1], 15, v[0:1]
	v_lshl_add_u64 v[2:3], s[62:63], 0, v[0:1]
	s_nop 0
	v_readfirstlane_b32 s4, v2
	v_readfirstlane_b32 s5, v3
	s_nop 4
	global_load_dword v36, v4, s[4:5]
	v_readfirstlane_b32 s100, v216
	v_and_b32_e32 v250, 31, v217
	v_lshrrev_b32_e32 v251, 5, v217
	v_lshlrev_b32_e32 v250, 11, v250
	v_lshl_or_b32 v250, v251, 4, v250
	s_lshr_b32 s100, s100, 6
	s_lshl_b32 s100, s100, 5
	s_lshr_b32 s101, s16, 4
	s_lshl_b32 s101, s101, 13
	s_add_i32 s100, s100, s101
	s_lshl_b32 s101, s17, 8
	s_add_i32 s100, s100, s101
	s_lshl_b32 s100, s100, 11
	s_and_b32 s101, s16, 15
	s_lshl_b32 s101, s101, 7
	s_add_u32 s100, s100, s101
	s_add_u32 s98, s20, s100
	s_addc_u32 s99, s21, 0
	global_load_dwordx4 v[124:127], v250, s[98:99]
	global_load_dwordx4 v[120:123], v250, s[98:99] offset:32
	global_load_dwordx4 v[116:119], v250, s[98:99] offset:64
	global_load_dwordx4 v[112:115], v250, s[98:99] offset:96
	s_cmp_lt_i32 s32, 0
	s_cbranch_scc0 .Lla_fast
	v_cmp_gt_u32_e64 s[4:5], s70, v217
	v_mov_b32_e32 v4, 0
	s_and_saveexec_b64 s[18:19], s[4:5]
	s_cbranch_execz .LBB0_847
	v_readfirstlane_b32 s4, v2
	v_readfirstlane_b32 s5, v3
	s_nop 4
	global_load_dword v4, v221, s[4:5] offset:252

; template<int THRL> __device__ __forceinline__ void fox_attn_phase(char*lds,const bf16*Q,const bf16*K,const bf16*V,bf16*O,const bf16*G,const float*__restrict__ cumf,unsigned*counter,float TH,float mfix){
;     ...
;     const float cqr=cf[q0+wid*QBLK+(lane&31)];
;     int t0;
;     { bool k0=true,k1=true;
;       if(lane<nb) k0=(cref-e0)>=-TH;
;       if(lane+64<nb) k1=(cref-e1)>=-TH;
;       const unsigned long long m0=__ballot(k0), m1=__ballot(k1);
;       int first=m0?__builtin_ctzll(m0):(m1?64+__builtin_ctzll(m1):128); if(first>nb)first=nb;
;       t0=__builtin_amdgcn_readfirstlane(first&~1); }
.Lla_fast:
	v_lshl_add_u64 v[2:3], v[2:3], 0, s[40:41]
	v_lshl_add_u64 v[2:3], v[202:203], 2, v[2:3]
	global_load_dword v37, v[2:3], off
	s_cmp_lt_i32 s32, 0
	s_cbranch_scc1 .Lla_orig
	s_mov_b32 s18, s32
	s_lshl_b32 s40, s17, 8
	s_branch .LBB0_852
.Lla_orig:
	s_waitcnt vmcnt(1)
	v_sub_f32_e32 v2, v36, v4
	v_cmp_ge_f32_e64 s[4:5], v2, -v218
	v_sub_f32_e32 v2, v36, v5
	s_or_b64 s[4:5], vcc, s[4:5]
	v_cmp_ge_f32_e64 s[14:15], v2, -v218
	s_or_b64 s[14:15], s[36:37], s[14:15]
	v_cndmask_b32_e64 v2, 0, 1, s[4:5]
	v_cmp_ne_u32_e32 vcc, 0, v2
	v_cndmask_b32_e64 v2, 0, 1, s[14:15]
	v_cmp_ne_u32_e64 s[36:37], 0, v2
	s_cbranch_vccz .LBB0_920
	s_ff1_i32_b64 s18, vcc
	s_lshl_b32 s40, s17, 8
	s_cbranch_execnz .LBB0_852

; __device__ __forceinline__ int crow(int r,int hi){return (r&3)+8*(r>>2)+4*hi;}
; template<int THRL> __device__ __forceinline__ void attn_unit(int b,int h,int qb,int t0,float cqv,float mfix,const float*__restrict__ cf,float cref,unsigned*counter,const bf16*Q,const bf16*__restrict__ K,const bf16*__restrict__ V,bf16*O,const bf16*__restrict__ G,char*shm){
;     ...
;   int unext_=0; if(tid==0) unext_=(int)atomicAdd(counter,1u);
;   {auto rr=__builtin_amdgcn_permlane32_swap(__float_as_uint(l_reg),__float_as_uint(l_reg),false,false);l_reg=__uint_as_float(rr[0])+__uint_as_float(rr[1]);}
;   if(hi==0)wsf[32+r32]=l_reg;asm volatile("s_waitcnt lgkmcnt(0)":::"memory");
;   float rli[16];
;   #pragma unroll
;   for(int r=0;r<16;++r)rli[r]=__builtin_amdgcn_rcpf(wsf[32+crow(r,hi)]);
;   bf16*Ow=O+(rowbase+q0+wid*QBLK)*DM+h*D;
;   { bf16*stg=(bf16*)(shm+LDS_OST)+wid*2048;
;     #pragma unroll
;     for(int r=0;r<16;++r){const int orow=crow(r,hi);
;       #pragma unroll
;       for(int d0=0;d0<2;++d0)stg[orow*64+d0*32+r32]=__float2bfloat16(o[d0][r]*rli[r]);}
;     asm volatile("s_waitcnt lgkmcnt(0)":::"memory");
;     const bf16*Gw=G+(rowbase+q0+wid*QBLK)*DM+h*D;
;     u32x4 gv4[4];
;     #pragma unroll
;     for(int i=0;i<4;++i)gv4[i]=*(const u32x4*)(Gw+(long)(i*8+(lane>>3))*DM+(lane&7)*8);
.LBB0_874:
	v_cmp_eq_u32_e64 s[100:101], 0, v226
	v_mov_b32_e32 v252, 1
	s_and_saveexec_b64 s[100:101], s[100:101]
	global_atomic_add v252, v205, v252, s[10:11] offset:256 sc0
	s_mov_b64 exec, s[100:101]
	s_lshl_b64 s[98:99], s[38:39], 1
	v_lshlrev_b32_e32 v196, 1, v225
	v_lshlrev_b32_e32 v197, 8, v224
	s_add_u32 s98, s2, s98
	s_addc_u32 s99, s3, s99
	v_and_b32_e32 v196, 0x70, v196
	v_and_b32_e32 v197, 0x3800, v197
	s_add_u32 s98, s98, s52
	s_addc_u32 s99, s99, s53
	v_add_u32_e32 v196, v196, v197
	v_add_u32_e32 v197, 0x4000, v196
	v_add_u32_e32 v198, 0x8000, v196
	v_add_u32_e32 v199, 0xc000, v196
	global_load_dwordx4 v[180:183], v196, s[98:99]
	global_load_dwordx4 v[184:187], v197, s[98:99]
	global_load_dwordx4 v[188:191], v198, s[98:99]
	global_load_dwordx4 v[192:195], v199, s[98:99]
	s_cmp_lg_u32 0, -1
	s_cselect_b32 s4, 0, 0
	s_addk_i32 s4, 0x6000
	v_add3_u32 v33, v234, s4, v232
	v_add_u32_e32 v38, s72, v235
	ds_read_b64_tr_b16 v[176:177], v38 offset:24576
	ds_read_b64_tr_b16 v[178:179], v38 offset:25088
	v_add_f32_e32 v34, v64, v65
	v_add_f32_e32 v34, v66, v34
	v_add_f32_e32 v34, v67, v34
	v_add_f32_e32 v34, v68, v34
	v_add_f32_e32 v34, v69, v34
	v_cvt_pk_bf16_f32 v128, v64, v65
	v_cvt_pk_bf16_f32 v129, v66, v67
	s_waitcnt lgkmcnt(3)
	v_mfma_f32_32x32x16_bf16 v[96:111], v[172:175], v[124:127], 0
	ds_read_b64_tr_b16 v[172:173], v38 offset:28672
	ds_read_b64_tr_b16 v[174:175], v38 offset:29184
	v_add_f32_e32 v34, v70, v34
	v_add_f32_e32 v34, v71, v34
	v_add_f32_e32 v34, v72, v34
	v_add_f32_e32 v39, v73, v34
	v_cvt_pk_bf16_f32 v130, v68, v69
	v_cvt_pk_bf16_f32 v131, v70, v71
	s_waitcnt lgkmcnt(4)
	v_mfma_f32_32x32x16_bf16 v[80:95], v[164:167], v[124:127], 0
	ds_read_b64_tr_b16 v[34:35], v38 offset:25600
	ds_read_b64_tr_b16 v[36:37], v38 offset:26112
	v_add_f32_e32 v39, v74, v39
	v_add_f32_e32 v39, v75, v39
	v_add_f32_e32 v39, v76, v39
	v_add_f32_e32 v39, v77, v39
	v_cvt_pk_bf16_f32 v136, v72, v73
	v_cvt_pk_bf16_f32 v137, v74, v75
	v_mfma_f32_32x32x16_bf16 v[96:111], v[168:171], v[120:123], v[96:111]
	ds_read_b64_tr_b16 v[70:71], v38 offset:29696
	ds_read_b64_tr_b16 v[72:73], v38 offset:30208
	v_add_f32_e32 v39, v78, v39
	v_add_f32_e32 v39, v79, v39
	v_add_f32_e32 v39, v48, v39
	v_add_f32_e32 v39, v49, v39
	v_cvt_pk_bf16_f32 v138, v76, v77
	v_cvt_pk_bf16_f32 v139, v78, v79
	v_mfma_f32_32x32x16_bf16 v[80:95], v[160:163], v[120:123], v[80:95]
	ds_read_b64_tr_b16 v[120:121], v38 offset:26624
	ds_read_b64_tr_b16 v[122:123], v38 offset:27136
	v_add_f32_e32 v39, v50, v39
	v_add_f32_e32 v39, v51, v39
	v_add_f32_e32 v39, v52, v39
	v_add_f32_e32 v39, v53, v39
	v_cvt_pk_bf16_f32 v132, v48, v49
	v_cvt_pk_bf16_f32 v133, v50, v51
	v_mfma_f32_32x32x16_bf16 v[96:111], v[156:159], v[116:119], v[96:111]
	ds_read_b64_tr_b16 v[66:67], v38 offset:30720
	ds_read_b64_tr_b16 v[68:69], v38 offset:31232
	v_add_f32_e32 v39, v54, v39
	v_add_f32_e32 v39, v55, v39
	v_add_f32_e32 v39, v56, v39
	v_add_f32_e32 v39, v57, v39
	v_cvt_pk_bf16_f32 v134, v52, v53
	v_cvt_pk_bf16_f32 v135, v54, v55
	v_mfma_f32_32x32x16_bf16 v[80:95], v[152:155], v[116:119], v[80:95]
	ds_read_b64_tr_b16 v[74:75], v38 offset:27648
	ds_read_b64_tr_b16 v[76:77], v38 offset:28160
	v_add_f32_e32 v39, v58, v39
	v_add_f32_e32 v39, v59, v39
	v_add_f32_e32 v39, v60, v39
	v_add_f32_e32 v39, v61, v39
	v_cvt_pk_bf16_f32 v140, v56, v57
	v_cvt_pk_bf16_f32 v141, v58, v59
	v_mfma_f32_32x32x16_bf16 v[96:111], v[148:151], v[112:115], v[96:111]
	ds_read_b64_tr_b16 v[116:117], v38 offset:31744
	ds_read_b64_tr_b16 v[118:119], v38 offset:32256
	v_add_f32_e32 v38, v62, v39
	v_add_f32_e32 v38, v63, v38
	v_add_f32_e32 v78, 0, v38
	v_cvt_pk_bf16_f32 v142, v60, v61
	v_cvt_pk_bf16_f32 v143, v62, v63
	v_mfma_f32_32x32x16_bf16 v[80:95], v[144:147], v[112:115], v[80:95]
	s_lshl_b32 s4, s67, 2
	s_add_i32 s4, s4, 0
	s_add_i32 s4, s4, 0x14800
	v_add_u32_e32 v38, s4, v230
	v_add_u32_e32 v79, 0xffffff00, v38
	ds_read_b128 v[38:41], v79
	ds_read_b128 v[42:45], v79 offset:32
	ds_read_b128 v[46:49], v79 offset:64
	ds_read_b128 v[50:53], v79 offset:96
	ds_read_b128 v[54:57], v79 offset:128
	ds_read_b128 v[58:61], v79 offset:160
	ds_read_b128 v[62:65], v79 offset:192
	ds_read_b128 v[112:115], v79 offset:224
	s_waitcnt lgkmcnt(7)
	v_sub_f32_e32 v39, v206, v39
	s_waitcnt lgkmcnt(3)
	v_sub_f32_e32 v55, v206, v55
	v_sub_f32_e32 v54, v206, v54
	v_pk_add_f32 v[54:55], v[80:81], v[54:55]
	v_or_b32_e32 v80, 0xe0, v228
	v_sub_f32_e32 v38, v206, v38
	v_or_b32_e32 v79, 0xc0, v228
	v_cmp_le_i32_e32 vcc, v80, v231
	v_pk_add_f32 v[38:39], v[96:97], v[38:39]
	v_sub_f32_e32 v41, v206, v41
	v_cndmask_b32_e32 v80, v223, v54, vcc
	v_cmp_lt_i32_e32 vcc, v79, v231
	v_sub_f32_e32 v40, v206, v40
	s_waitcnt lgkmcnt(2)
	v_sub_f32_e32 v61, v206, v61
	v_cndmask_b32_e32 v81, v223, v39, vcc
	v_cmp_le_i32_e32 vcc, v79, v231
	v_sub_f32_e32 v60, v206, v60
	v_pk_add_f32 v[40:41], v[98:99], v[40:41]
	v_cndmask_b32_e32 v79, v223, v38, vcc
	v_or_b32_e32 v38, 0xe1, v228
	v_cmp_le_i32_e32 vcc, v38, v231
	v_or_b32_e32 v38, 0xc2, v228
	v_sub_f32_e32 v57, v206, v57
	v_sub_f32_e32 v56, v206, v56
	v_pk_add_f32 v[60:61], v[86:87], v[60:61]
	v_cndmask_b32_e32 v86, v223, v55, vcc
	v_cmp_le_i32_e32 vcc, v38, v231
	v_or_b32_e32 v38, 0xe2, v228
	s_waitcnt lgkmcnt(1)
; #define SBAR() __builtin_amdgcn_sched_barrier(0)
; #define WAIT_BAR(N) asm volatile("s_waitcnt vmcnt(" #N ") lgkmcnt(0)\n\ts_barrier":::"memory")
;   #define RESC() do{}while(0)
;   #define ROT() do{sl_prev=sl_cur;sl_cur=sl_next;sl_next=(sl_next==(NSLOT-1)*SLOTB)?0:sl_next+SLOTB;}while(0)
;   #define PKW(P,B) cvtpk_s(P[B],P[B+1])
;   #define ENDW(tt) do{ if((tt)+3<NT){WAIT_BAR(2);} else if((tt)+2<NT){WAIT_BAR(1);} else {WAIT_BAR(0);} }while(0)
; __device__ __forceinline__ void cmask(f32x16&p0,f32x16&p1,int jb,int qrel,int hi){
;   const float NEG=-INFINITY; int kb=64*jb+4*hi;
;   #pragma unroll
;   for(int r=0;r<16;++r){int kv=kb+(r&3)+8*(r>>2); if(kv>qrel)p0[r]=NEG; if(kv+32>qrel)p1[r]=NEG;}
; }
; template<int THRL> __device__ __forceinline__ void attn_unit(int b,int h,int qb,int t0,float cqv,float mfix,const float*__restrict__ cf,float cref,unsigned*counter,const bf16*Q,const bf16*__restrict__ K,const bf16*__restrict__ V,bf16*O,const bf16*__restrict__ G,char*shm){
;     ...
;   int t=1;
;     ...
;   for(;t+5<NT;t+=2){
;     STEP(pB0,pB1,pA0,pA1,t,true,true,true);     WAIT_BAR(2); RESC(); ROT();
;     STEP(pA0,pA1,pB0,pB1,t+1,true,true,true);   WAIT_BAR(2); RESC(); ROT();
;   }
;     ...
;   for(;t+1<NT;t+=2){
;     STEP(pB0,pB1,pA0,pA1,t,(t+3<NT),(t+1<NT),(t+1<NT));       ENDW(t);   RESC(); ROT();
;     STEP(pA0,pA1,pB0,pB1,t+1,(t+4<NT),(t+2<NT),(t+2<NT));     ENDW(t+1); RESC(); ROT();
;   }
;   STEP(pB0,pB1,pA0,pA1,NT-1,false,false,false); RESC();
;   { float sacc=pB0[0]+pB0[1]; _Pragma("unroll") for(int r=2;r<16;++r)sacc+=pB0[r]; _Pragma("unroll") for(int r=0;r<16;++r)sacc+=pB1[r]; l_reg+=sacc;
;     pw0=(u32x4){PKW(pB0,0),PKW(pB0,2),PKW(pB0,4),PKW(pB0,6)};pw1=(u32x4){PKW(pB0,8),PKW(pB0,10),PKW(pB0,12),PKW(pB0,14)};pw2=(u32x4){PKW(pB1,0),PKW(pB1,2),PKW(pB1,4),PKW(pB1,6)};pw3=(u32x4){PKW(pB1,8),PKW(pB1,10),PKW(pB1,12),PKW(pB1,14)};
;     SBAR(); pv(o,vb0+sl_cur,PAF(0),PAF(1),PAF(2),PAF(3)); }
	v_sub_f32_e32 v63, v206, v63
	v_sub_f32_e32 v62, v206, v62
	v_pk_add_f32 v[56:57], v[82:83], v[56:57]
	v_cndmask_b32_e32 v87, v223, v40, vcc
	v_cmp_le_i32_e32 vcc, v38, v231
	v_or_b32_e32 v38, 0xc3, v228
	v_pk_add_f32 v[62:63], v[88:89], v[62:63]
	v_cndmask_b32_e32 v88, v223, v56, vcc
	v_cmp_le_i32_e32 vcc, v38, v231
	v_or_b32_e32 v38, 0xe3, v228
	v_sub_f32_e32 v43, v206, v43
	v_sub_f32_e32 v42, v206, v42
	v_sub_f32_e32 v65, v206, v65
	v_sub_f32_e32 v64, v206, v64
	v_cndmask_b32_e32 v89, v223, v41, vcc
	v_cmp_le_i32_e32 vcc, v38, v231
	v_or_b32_e32 v38, 0xc8, v228
	v_pk_add_f32 v[42:43], v[100:101], v[42:43]
	v_sub_f32_e32 v59, v206, v59
	v_sub_f32_e32 v58, v206, v58
	v_pk_add_f32 v[64:65], v[90:91], v[64:65]
	v_cndmask_b32_e32 v90, v223, v57, vcc
	v_cmp_le_i32_e32 vcc, v38, v231
	v_or_b32_e32 v38, 0xe8, v228
	v_pk_add_f32 v[58:59], v[84:85], v[58:59]
	v_cndmask_b32_e32 v54, v223, v42, vcc
	v_cmp_le_i32_e32 vcc, v38, v231
	v_or_b32_e32 v39, 0xc9, v228
	v_sub_f32_e32 v45, v206, v45
	v_cndmask_b32_e32 v38, v223, v58, vcc
	v_cmp_le_i32_e32 vcc, v39, v231
	v_or_b32_e32 v39, 0xe9, v228
	v_sub_f32_e32 v44, v206, v44
	v_cndmask_b32_e32 v55, v223, v43, vcc
	v_cmp_le_i32_e32 vcc, v39, v231
	v_or_b32_e32 v40, 0xca, v228
	v_pk_add_f32 v[44:45], v[102:103], v[44:45]
	v_cndmask_b32_e32 v39, v223, v59, vcc
	v_cmp_le_i32_e32 vcc, v40, v231
	v_or_b32_e32 v40, 0xea, v228
	v_or_b32_e32 v41, 0xcb, v228
	v_cndmask_b32_e32 v56, v223, v44, vcc
	v_cmp_le_i32_e32 vcc, v40, v231
	v_sub_f32_e32 v47, v206, v47
	v_sub_f32_e32 v46, v206, v46
	v_cndmask_b32_e32 v40, v223, v60, vcc
	v_cmp_le_i32_e32 vcc, v41, v231
	v_or_b32_e32 v41, 0xeb, v228
	v_or_b32_e32 v42, 0xd0, v228
	v_cndmask_b32_e32 v57, v223, v45, vcc
	v_cmp_le_i32_e32 vcc, v41, v231
	v_pk_add_f32 v[46:47], v[104:105], v[46:47]
	v_or_b32_e32 v43, 0xd1, v228
	v_cndmask_b32_e32 v41, v223, v61, vcc
	v_cmp_le_i32_e32 vcc, v42, v231
	v_or_b32_e32 v42, 0xf0, v228
	v_sub_f32_e32 v49, v206, v49
	v_cndmask_b32_e32 v58, v223, v46, vcc
	v_cmp_le_i32_e32 vcc, v42, v231
	v_sub_f32_e32 v48, v206, v48
	v_or_b32_e32 v44, 0xd2, v228
	v_cndmask_b32_e32 v42, v223, v62, vcc
	v_cmp_le_i32_e32 vcc, v43, v231
	v_or_b32_e32 v43, 0xf1, v228
	v_pk_add_f32 v[48:49], v[106:107], v[48:49]
	v_cndmask_b32_e32 v59, v223, v47, vcc
	v_cmp_le_i32_e32 vcc, v43, v231
	v_or_b32_e32 v45, 0xd3, v228
	v_sub_f32_e32 v51, v206, v51
	v_cndmask_b32_e32 v43, v223, v63, vcc
	v_cmp_le_i32_e32 vcc, v44, v231
	v_or_b32_e32 v44, 0xf2, v228
	v_sub_f32_e32 v50, v206, v50
	v_cndmask_b32_e32 v60, v223, v48, vcc
	v_cmp_le_i32_e32 vcc, v44, v231
	v_or_b32_e32 v46, 0xd8, v228
	v_pk_add_f32 v[50:51], v[108:109], v[50:51]
	v_cndmask_b32_e32 v44, v223, v64, vcc
	v_cmp_le_i32_e32 vcc, v45, v231
	v_or_b32_e32 v45, 0xf3, v228
	s_waitcnt lgkmcnt(0)
	v_sub_f32_e32 v99, v206, v113
	v_cndmask_b32_e32 v61, v223, v49, vcc
	v_cmp_le_i32_e32 vcc, v45, v231
	v_sub_f32_e32 v98, v206, v112
	v_pk_add_f32 v[82:83], v[92:93], v[98:99]
	v_cndmask_b32_e32 v45, v223, v65, vcc
	v_cmp_le_i32_e32 vcc, v46, v231
	v_or_b32_e32 v46, 0xf8, v228
	v_or_b32_e32 v47, 0xd9, v228
	v_cndmask_b32_e32 v62, v223, v50, vcc
	v_cmp_le_i32_e32 vcc, v46, v231
	v_sub_f32_e32 v53, v206, v53
	v_sub_f32_e32 v52, v206, v52
	v_cndmask_b32_e32 v46, v223, v82, vcc
	v_cmp_le_i32_e32 vcc, v47, v231
	v_or_b32_e32 v47, 0xf9, v228
	v_or_b32_e32 v48, 0xda, v228
	v_cndmask_b32_e32 v63, v223, v51, vcc
	v_cmp_le_i32_e32 vcc, v47, v231
	v_pk_add_f32 v[52:53], v[110:111], v[52:53]
	v_sub_f32_e32 v97, v206, v115
	v_sub_f32_e32 v96, v206, v114
	v_cndmask_b32_e32 v47, v223, v83, vcc
	v_cmp_le_i32_e32 vcc, v48, v231
	v_or_b32_e32 v48, 0xfa, v228
	v_pk_add_f32 v[84:85], v[94:95], v[96:97]
	v_cndmask_b32_e32 v64, v223, v52, vcc
	v_cmp_le_i32_e32 vcc, v48, v231
	v_or_b32_e32 v49, 0xdb, v228
	s_nop 0
	v_cndmask_b32_e32 v48, v223, v84, vcc
	v_cmp_le_i32_e32 vcc, v49, v231
	v_or_b32_e32 v49, 0xfb, v228
	s_nop 0
	v_cndmask_b32_e32 v65, v223, v53, vcc
	v_cmp_le_i32_e32 vcc, v49, v231
	s_nop 1
	v_cndmask_b32_e32 v49, v223, v85, vcc
	v_mfma_f32_32x32x16_bf16 v[0:15], v[128:131], v[176:179], v[0:15]
	v_exp_f32_e32 v50, v79
	v_exp_f32_e32 v51, v81
	v_exp_f32_e32 v52, v87
	v_exp_f32_e32 v53, v89
	v_mfma_f32_32x32x16_bf16 v[16:31], v[128:131], v[172:175], v[16:31]
	v_exp_f32_e32 v54, v54
	v_exp_f32_e32 v55, v55
	v_exp_f32_e32 v56, v56
	v_exp_f32_e32 v57, v57
	v_mfma_f32_32x32x16_bf16 v[0:15], v[136:139], v[34:37], v[0:15]
	v_exp_f32_e32 v58, v58
	v_exp_f32_e32 v59, v59
	v_exp_f32_e32 v60, v60
	v_exp_f32_e32 v61, v61
	v_mfma_f32_32x32x16_bf16 v[16:31], v[136:139], v[70:73], v[16:31]
	v_exp_f32_e32 v62, v62
	v_exp_f32_e32 v63, v63
	v_exp_f32_e32 v64, v64
	v_exp_f32_e32 v65, v65
	v_mfma_f32_32x32x16_bf16 v[0:15], v[132:135], v[120:123], v[0:15]
	v_exp_f32_e32 v34, v80
	v_exp_f32_e32 v35, v86
	v_exp_f32_e32 v36, v88
	v_exp_f32_e32 v37, v90
	v_mfma_f32_32x32x16_bf16 v[16:31], v[132:135], v[66:69], v[16:31]
	v_exp_f32_e32 v38, v38
	v_exp_f32_e32 v39, v39
	v_exp_f32_e32 v40, v40
	v_exp_f32_e32 v41, v41
	v_mfma_f32_32x32x16_bf16 v[0:15], v[140:143], v[74:77], v[0:15]
	v_exp_f32_e32 v42, v42
	v_exp_f32_e32 v43, v43
	v_exp_f32_e32 v44, v44
	v_exp_f32_e32 v45, v45
	v_mfma_f32_32x32x16_bf16 v[16:31], v[140:143], v[116:119], v[16:31]
	v_exp_f32_e32 v46, v46
	v_exp_f32_e32 v47, v47
	v_exp_f32_e32 v48, v48
	v_exp_f32_e32 v49, v49
	v_cvt_pk_bf16_f32 v66, v50, v51
	v_cvt_pk_bf16_f32 v67, v52, v53
	v_cvt_pk_bf16_f32 v68, v54, v55
	v_cvt_pk_bf16_f32 v69, v56, v57
	v_cvt_pk_bf16_f32 v70, v58, v59
	v_cvt_pk_bf16_f32 v71, v60, v61
	v_cvt_pk_bf16_f32 v72, v62, v63
	v_cvt_pk_bf16_f32 v73, v64, v65
	v_cvt_pk_bf16_f32 v74, v34, v35
	v_cvt_pk_bf16_f32 v75, v36, v37
	v_cvt_pk_bf16_f32 v76, v38, v39
	v_cvt_pk_bf16_f32 v77, v40, v41
	v_cvt_pk_bf16_f32 v80, v42, v43
	v_cvt_pk_bf16_f32 v81, v44, v45
	v_cvt_pk_bf16_f32 v82, v46, v47
	v_cvt_pk_bf16_f32 v83, v48, v49
	v_add3_u32 v33, v33, v229, s59
	ds_read_b64_tr_b16 v[84:85],v33 offset:0
	ds_read_b64_tr_b16 v[86:87],v33 offset:512
	ds_read_b64_tr_b16 v[88:89],v33 offset:1024
	ds_read_b64_tr_b16 v[90:91],v33 offset:1536
	ds_read_b64_tr_b16 v[92:93],v33 offset:2048
	ds_read_b64_tr_b16 v[94:95],v33 offset:2560
	ds_read_b64_tr_b16 v[96:97],v33 offset:3072
	ds_read_b64_tr_b16 v[98:99],v33 offset:3584
	s_waitcnt lgkmcnt(0)
; __device__ __forceinline__ int crow(int r,int hi){return (r&3)+8*(r>>2)+4*hi;}
; #define SBAR() __builtin_amdgcn_sched_barrier(0)
;   #define PKW(P,B) cvtpk_s(P[B],P[B+1])
; template<int THRL> __device__ __forceinline__ void attn_unit(int b,int h,int qb,int t0,float cqv,float mfix,const float*__restrict__ cf,float cref,unsigned*counter,const bf16*Q,const bf16*__restrict__ K,const bf16*__restrict__ V,bf16*O,const bf16*__restrict__ G,char*shm){
;     ...
;   { float sacc=pB0[0]+pB0[1]; _Pragma("unroll") for(int r=2;r<16;++r)sacc+=pB0[r]; _Pragma("unroll") for(int r=0;r<16;++r)sacc+=pB1[r]; l_reg+=sacc;
;     pw0=(u32x4){PKW(pB0,0),PKW(pB0,2),PKW(pB0,4),PKW(pB0,6)};pw1=(u32x4){PKW(pB0,8),PKW(pB0,10),PKW(pB0,12),PKW(pB0,14)};pw2=(u32x4){PKW(pB1,0),PKW(pB1,2),PKW(pB1,4),PKW(pB1,6)};pw3=(u32x4){PKW(pB1,8),PKW(pB1,10),PKW(pB1,12),PKW(pB1,14)};
;     SBAR(); pv(o,vb0+sl_cur,PAF(0),PAF(1),PAF(2),PAF(3)); }
;     ...
;   int unext_=0; if(tid==0) unext_=(int)atomicAdd(counter,1u);
;   {auto rr=__builtin_amdgcn_permlane32_swap(__float_as_uint(l_reg),__float_as_uint(l_reg),false,false);l_reg=__uint_as_float(rr[0])+__uint_as_float(rr[1]);}
;   if(hi==0)wsf[32+r32]=l_reg;asm volatile("s_waitcnt lgkmcnt(0)":::"memory");
;   float rli[16];
;   #pragma unroll
;   for(int r=0;r<16;++r)rli[r]=__builtin_amdgcn_rcpf(wsf[32+crow(r,hi)]);
;   bf16*Ow=O+(rowbase+q0+wid*QBLK)*DM+h*D;
;   { bf16*stg=(bf16*)(shm+LDS_OST)+wid*2048;
;     #pragma unroll
;     for(int r=0;r<16;++r){const int orow=crow(r,hi);
;       #pragma unroll
;       for(int d0=0;d0<2;++d0)stg[orow*64+d0*32+r32]=__float2bfloat16(o[d0][r]*rli[r]);}
	s_nop 0
	v_mfma_f32_32x32x16_bf16 v[0:15], v[66:69], v[84:87], v[0:15]
	ds_read_b64_tr_b16 v[84:85],v33 offset:4096
	ds_read_b64_tr_b16 v[86:87],v33 offset:4608
	v_mfma_f32_32x32x16_bf16 v[0:15], v[70:73], v[88:91], v[0:15]
	ds_read_b64_tr_b16 v[88:89],v33 offset:5120
	ds_read_b64_tr_b16 v[90:91],v33 offset:5632
	v_mfma_f32_32x32x16_bf16 v[0:15], v[74:77], v[92:95], v[0:15]
	ds_read_b64_tr_b16 v[92:93],v33 offset:6144
	ds_read_b64_tr_b16 v[94:95],v33 offset:6656
	v_mfma_f32_32x32x16_bf16 v[0:15], v[80:83], v[96:99], v[0:15]
	ds_read_b64_tr_b16 v[96:97],v33 offset:7168
	ds_read_b64_tr_b16 v[98:99],v33 offset:7680
	s_waitcnt lgkmcnt(0)
	v_mfma_f32_32x32x16_bf16 v[16:31], v[66:69], v[84:87], v[16:31]
	v_cmp_eq_u32_e32 vcc, 0, v226
	v_mov_b32_e32 v33, 0
	v_mfma_f32_32x32x16_bf16 v[16:31], v[70:73], v[88:91], v[16:31]
	v_mfma_f32_32x32x16_bf16 v[16:31], v[74:77], v[92:95], v[16:31]
	v_mfma_f32_32x32x16_bf16 v[16:31], v[80:83], v[96:99], v[16:31]
	v_add_f32_e32 v50, v50, v51
	v_add_f32_e32 v50, v52, v50
	v_add_f32_e32 v50, v53, v50
	v_add_f32_e32 v50, v54, v50
	v_add_f32_e32 v50, v55, v50
	v_add_f32_e32 v50, v56, v50
	v_add_f32_e32 v50, v57, v50
	v_add_f32_e32 v50, v58, v50
	v_add_f32_e32 v50, v59, v50
	v_add_f32_e32 v50, v60, v50
	v_add_f32_e32 v50, v61, v50
	v_add_f32_e32 v50, v62, v50
	v_add_f32_e32 v50, v63, v50
	v_add_f32_e32 v50, v64, v50
	v_add_f32_e32 v50, v65, v50
	v_add_f32_e32 v34, v34, v50
	v_add_f32_e32 v34, v35, v34
	v_add_f32_e32 v34, v36, v34
	v_add_f32_e32 v34, v37, v34
	v_add_f32_e32 v34, v38, v34
	v_add_f32_e32 v34, v39, v34
	v_add_f32_e32 v34, v40, v34
	v_add_f32_e32 v34, v41, v34
	v_add_f32_e32 v34, v42, v34
	v_add_f32_e32 v34, v43, v34
	v_add_f32_e32 v34, v44, v34
	v_add_f32_e32 v34, v45, v34
	v_add_f32_e32 v34, v46, v34
	v_add_f32_e32 v34, v47, v34
	v_add_f32_e32 v34, v48, v34
	v_add_f32_e32 v34, v49, v34
	v_add_f32_e32 v32, v32, v78
	v_add_f32_e32 v32, v32, v34
	s_and_b32 s4, s66, 0x3fffffc0
	s_lshl_b32 s4, s4, 2
	v_mov_b32_e32 v34, v32
	s_add_i32 s16, s4, 0
	s_nop 0
	v_permlane32_swap_b32_e32 v32, v34
	v_cmp_gt_u32_e64 s[4:5], 32, v224
	s_and_saveexec_b64 s[18:19], s[4:5]
	v_lshl_add_u32 v35, v204, 2, s16
	v_add_f32_e32 v32, v32, v34
	ds_write_b32 v35, v32 offset:49280
	s_or_b64 exec, exec, s[18:19]
	s_waitcnt lgkmcnt(0)
	v_lshl_add_u32 v32, v228, 2, s16
	ds_read_b128 v[34:37], v32 offset:49280
	ds_read_b128 v[38:41], v32 offset:49312
	s_lshl_b64 s[4:5], s[38:39], 1
	s_add_u32 s14, s12, s4
	s_addc_u32 s15, s13, s5
	s_waitcnt lgkmcnt(1)
	v_rcp_f32_e32 v42, v34
	v_rcp_f32_e32 v43, v35
	v_rcp_f32_e32 v44, v36
	v_rcp_f32_e32 v45, v37
	s_waitcnt lgkmcnt(0)
	v_rcp_f32_e32 v46, v38
	ds_read_b128 v[34:37], v32 offset:49344
	v_rcp_f32_e32 v47, v39
	v_rcp_f32_e32 v48, v40
	v_rcp_f32_e32 v49, v41
	ds_read_b128 v[38:41], v32 offset:49376
	s_lshl_b32 s16, s65, 12
	s_waitcnt lgkmcnt(1)
	v_rcp_f32_e32 v32, v34
	v_rcp_f32_e32 v34, v35
	v_rcp_f32_e32 v35, v36
	v_rcp_f32_e32 v36, v37
	s_waitcnt lgkmcnt(0)
	v_rcp_f32_e32 v37, v38
	v_rcp_f32_e32 v38, v39
	v_rcp_f32_e32 v39, v40
	v_rcp_f32_e32 v40, v41
	s_add_i32 s16, s16, 0
	v_lshlrev_b32_e32 v41, 1, v204
	v_lshlrev_b32_e32 v50, 9, v227
	v_mul_f32_e32 v0, v0, v42
	v_add3_u32 v41, s16, v41, v50
	v_cvt_pk_bf16_f32 v0, v0, s0
	ds_write_b16 v41, v0 offset:51200
	v_mul_f32_e32 v0, v16, v42
	v_cvt_pk_bf16_f32 v0, v0, s0
	ds_write_b16 v41, v0 offset:51264
	v_mul_f32_e32 v0, v1, v43
	v_cvt_pk_bf16_f32 v0, v0, s0
	ds_write_b16 v41, v0 offset:51328
	v_mul_f32_e32 v0, v17, v43
	v_cvt_pk_bf16_f32 v0, v0, s0
	ds_write_b16 v41, v0 offset:51392
	v_mul_f32_e32 v0, v2, v44
	v_cvt_pk_bf16_f32 v0, v0, s0
	ds_write_b16 v41, v0 offset:51456
	v_mul_f32_e32 v0, v18, v44
	v_cvt_pk_bf16_f32 v0, v0, s0
	ds_write_b16 v41, v0 offset:51520
	v_mul_f32_e32 v0, v3, v45
	v_cvt_pk_bf16_f32 v0, v0, s0
	ds_write_b16 v41, v0 offset:51584
	v_mul_f32_e32 v0, v19, v45
	v_cvt_pk_bf16_f32 v0, v0, s0
	ds_write_b16 v41, v0 offset:51648
	v_mul_f32_e32 v0, v4, v46
	v_cvt_pk_bf16_f32 v0, v0, s0
	ds_write_b16 v41, v0 offset:52224
	v_mul_f32_e32 v0, v20, v46
	v_cvt_pk_bf16_f32 v0, v0, s0
	ds_write_b16 v41, v0 offset:52288
	v_mul_f32_e32 v0, v5, v47
	v_cvt_pk_bf16_f32 v0, v0, s0
	ds_write_b16 v41, v0 offset:52352
	v_mul_f32_e32 v0, v21, v47
	v_cvt_pk_bf16_f32 v0, v0, s0
	ds_write_b16 v41, v0 offset:52416
	v_mul_f32_e32 v0, v6, v48
	v_cvt_pk_bf16_f32 v0, v0, s0
	ds_write_b16 v41, v0 offset:52480
	v_mul_f32_e32 v0, v22, v48
	v_cvt_pk_bf16_f32 v0, v0, s0
	ds_write_b16 v41, v0 offset:52544
	v_mul_f32_e32 v0, v7, v49
	v_cvt_pk_bf16_f32 v0, v0, s0
	ds_write_b16 v41, v0 offset:52608
	v_mul_f32_e32 v0, v23, v49
	v_cvt_pk_bf16_f32 v0, v0, s0
	ds_write_b16 v41, v0 offset:52672
	v_mul_f32_e32 v0, v8, v32
	v_cvt_pk_bf16_f32 v0, v0, s0
	ds_write_b16 v41, v0 offset:53248
	v_mul_f32_e32 v0, v24, v32
	v_cvt_pk_bf16_f32 v0, v0, s0
	ds_write_b16 v41, v0 offset:53312
	v_mul_f32_e32 v0, v9, v34
	v_cvt_pk_bf16_f32 v0, v0, s0
	ds_write_b16 v41, v0 offset:53376
	v_mul_f32_e32 v0, v25, v34
	v_cvt_pk_bf16_f32 v0, v0, s0
	ds_write_b16 v41, v0 offset:53440
	v_mul_f32_e32 v0, v10, v35
	v_cvt_pk_bf16_f32 v0, v0, s0
	ds_write_b16 v41, v0 offset:53504
	v_mul_f32_e32 v0, v26, v35
	v_cvt_pk_bf16_f32 v0, v0, s0
	ds_write_b16 v41, v0 offset:53568
	v_mul_f32_e32 v0, v11, v36
	v_cvt_pk_bf16_f32 v0, v0, s0
	ds_write_b16 v41, v0 offset:53632
	v_mul_f32_e32 v0, v27, v36
	v_cvt_pk_bf16_f32 v0, v0, s0
	ds_write_b16 v41, v0 offset:53696
	v_mul_f32_e32 v0, v12, v37
	v_cvt_pk_bf16_f32 v0, v0, s0
	ds_write_b16 v41, v0 offset:54272
	v_mul_f32_e32 v0, v28, v37
	v_cvt_pk_bf16_f32 v0, v0, s0
	ds_write_b16 v41, v0 offset:54336
	v_mul_f32_e32 v0, v13, v38
	v_cvt_pk_bf16_f32 v0, v0, s0
	ds_write_b16 v41, v0 offset:54400
	v_mul_f32_e32 v0, v29, v38
	v_cvt_pk_bf16_f32 v0, v0, s0
	ds_write_b16 v41, v0 offset:54464
	v_mul_f32_e32 v0, v14, v39
	v_cvt_pk_bf16_f32 v0, v0, s0
	ds_write_b16 v41, v0 offset:54528
	v_mul_f32_e32 v0, v30, v39
	v_cvt_pk_bf16_f32 v0, v0, s0
	ds_write_b16 v41, v0 offset:54592
	v_mul_f32_e32 v0, v15, v40
	v_cvt_pk_bf16_f32 v0, v0, s0
	ds_write_b16 v41, v0 offset:54656
	v_mul_f32_e32 v0, v31, v40
	s_add_u32 s4, s2, s4
	v_cvt_pk_bf16_f32 v0, v0, s0
	s_addc_u32 s5, s3, s5
	ds_write_b16 v41, v0 offset:54720
	s_add_u32 s4, s4, s52
	v_lshlrev_b32_e32 v0, 1, v225
	s_addc_u32 s5, s5, s53
	v_and_b32_e32 v204, 0x70, v0
	v_lshlrev_b32_e32 v2, 8, v224
	v_lshl_add_u64 v[0:1], s[4:5], 0, v[204:205]
	v_and_b32_e32 v2, 0x3800, v2
	v_mov_b32_e32 v3, v205
	s_waitcnt lgkmcnt(0)
; __device__ __forceinline__ unsigned cvtpk_s(float lo,float hi){f32x2_t v={lo,hi};bf16x2_t b=__builtin_convertvector(v,bf16x2_t);return __builtin_bit_cast(unsigned,b);}
; template<int THRL> __device__ __forceinline__ void attn_unit(int b,int h,int qb,int t0,float cqv,float mfix,const float*__restrict__ cf,float cref,unsigned*counter,const bf16*Q,const bf16*__restrict__ K,const bf16*__restrict__ V,bf16*O,const bf16*__restrict__ G,char*shm){
;     ...
;     const bf16*Gw=G+(rowbase+q0+wid*QBLK)*DM+h*D;
;     u32x4 gv4[4];
;     #pragma unroll
;     for(int i=0;i<4;++i)gv4[i]=*(const u32x4*)(Gw+(long)(i*8+(lane>>3))*DM+(lane&7)*8);
;     #pragma unroll
;     for(int i=0;i<4;++i){const int row=i*8+(lane>>3),ch=lane&7; const u32x4 v=*(const u32x4*)(stg+row*64+ch*8); const u32x4 gv=gv4[i]; u32x4 w;
;       #pragma unroll
;       for(int c=0;c<4;++c){ const float ol=__uint_as_float(v[c]<<16), oh=__uint_as_float(v[c]&0xffff0000u), gl=__uint_as_float(gv[c]<<16), gh=__uint_as_float(gv[c]&0xffff0000u);
;         const float rl=ol*gl*__builtin_amdgcn_rcpf(1.f+__expf(-gl)), rh=oh*gh*__builtin_amdgcn_rcpf(1.f+__expf(-gh)); w[c]=cvtpk_s(rl,rh); }
;       ATTN_STORE16(Ow+(long)row*DM+ch*8,w);} }
; template<int THRL> __device__ __forceinline__ void fox_attn_phase(char*lds,const bf16*Q,const bf16*K,const bf16*V,bf16*O,const bf16*G,const float*__restrict__ cumf,unsigned*counter,float TH,float mfix){
;     ...
;     const int u=shi[0];
;     if(u>=NQB*BATCH*NHEAD) break;
;     const int qb=NQB-1-(u&31), bh=sorted[u>>5], q0=qb*QB;
;     const float* cf=cumf+(long)bh*SEQ;
;     const float cref=cf[q0];
;     const int nb=4*qb; float e0=0.f,e1=0.f;
;     if(lane<nb) e0=cf[64*lane+63];
;     if(lane+64<nb) e1=cf[64*(lane+64)+63];
	v_lshl_add_u64 v[0:1], v[0:1], 0, v[2:3]
	s_waitcnt vmcnt(0)
	v_mov_b64_e32 v[14:15], v[180:181]
	v_mov_b64_e32 v[16:17], v[182:183]
	s_movk_i32 s4, 0x4000
	v_add_co_u32_e64 v2, s[4:5], s4, v0
	v_lshrrev_b32_e32 v32, 3, v224
	s_nop 0
	v_addc_co_u32_e64 v3, s[4:5], 0, v1, s[4:5]
	v_mov_b64_e32 v[8:9], v[184:185]
	v_mov_b64_e32 v[10:11], v[186:187]
	s_mov_b32 s4, 0x8000
	v_add_co_u32_e64 v2, s[4:5], s4, v0
	v_add_u32_e32 v34, s16, v204
	s_nop 0
	v_addc_co_u32_e64 v3, s[4:5], 0, v1, s[4:5]
	s_mov_b32 s4, 0xc000
	s_nop 0
	v_add_co_u32_e64 v0, s[4:5], s4, v0
	v_lshl_add_u32 v18, v32, 7, v34
	s_nop 0
	v_addc_co_u32_e64 v1, s[4:5], 0, v1, s[4:5]
	v_mov_b64_e32 v[4:5], v[188:189]
	v_mov_b64_e32 v[6:7], v[190:191]
	s_nop 0
	v_mov_b64_e32 v[0:1], v[192:193]
	v_mov_b64_e32 v[2:3], v[194:195]
	v_readfirstlane_b32 s98, v216
	s_lshr_b32 s98, s98, 6
	s_cmp_lg_u32 s98, 0
	s_cbranch_scc1 .Lla1_skip
	v_readfirstlane_b32 s98, v252
	s_cmp_gt_u32 s98, 0x3ff
	s_cbranch_scc1 .Lla1_skip
	s_lshr_b32 s100, s98, 5
	s_lshl_b32 s100, s100, 2
	s_add_i32 s100, s100, 0x1c8c0
	v_mov_b32_e32 v196, s100
	ds_read_b32 v196, v196
	s_andn2_b32 s99, 31, s98
	v_and_b32_e32 v197, 63, v216
	v_lshlrev_b32_e32 v197, 8, v197
	s_waitcnt lgkmcnt(0)
	v_readfirstlane_b32 s100, v196
	s_nop 1
	s_lshl_b32 s100, s100, 15
	s_add_u32 s100, s62, s100
	s_addc_u32 s101, s63, 0
	s_lshl_b32 s98, s99, 10
	v_mov_b32_e32 v198, s98
	global_load_dword v199, v198, s[100:101]
	global_load_dword v200, v197, s[100:101] offset:252
	v_add_u32_e32 v198, 0x4000, v197
	global_load_dword v201, v198, s[100:101] offset:252
.Lla1_skip:
	v_or_b32_e32 v35, 8, v32
	s_add_u32 s4, s14, s52
	s_addc_u32 s5, s15, s53
	v_lshl_add_u64 v[12:13], s[4:5], 0, v[204:205]
	v_lshlrev_b32_e32 v204, 11, v32
	v_lshlrev_b32_e32 v26, 16, v14
	v_and_b32_e32 v29, 0xffff0000, v14
	v_mul_f32_e32 v14, 0xbfb8aa3b, v26
	v_exp_f32_e32 v14, v14
	v_mul_f32_e32 v19, 0xbfb8aa3b, v29
	v_exp_f32_e32 v22, v19
	ds_read_b128 v[18:21], v18 offset:51200
	v_add_f32_e32 v14, 1.0, v14
	v_rcp_f32_e32 v30, v14
	v_add_f32_e32 v14, 1.0, v22
	v_rcp_f32_e32 v31, v14
	v_lshl_add_u32 v14, v35, 7, v34
	ds_read_b128 v[22:25], v14 offset:51200
	s_waitcnt lgkmcnt(1)
	v_and_b32_e32 v27, 0xffff0000, v18
	v_lshlrev_b32_e32 v28, 16, v18
	v_pk_mul_f32 v[26:27], v[28:29], v[26:27]
	v_lshlrev_b32_e32 v28, 16, v15
	v_pk_mul_f32 v[26:27], v[30:31], v[26:27]
	v_and_b32_e32 v31, 0xffff0000, v15
	v_mul_f32_e32 v14, 0xbfb8aa3b, v28
	v_exp_f32_e32 v15, v14
	v_mul_f32_e32 v14, 0xbfb8aa3b, v31
	v_exp_f32_e32 v18, v14
	v_cvt_pk_bf16_f32 v14, v26, v27
	v_add_f32_e32 v15, 1.0, v15
	v_rcp_f32_e32 v26, v15
	v_add_f32_e32 v15, 1.0, v18
	v_rcp_f32_e32 v27, v15
	v_and_b32_e32 v29, 0xffff0000, v19
	v_lshlrev_b32_e32 v30, 16, v19
	v_pk_mul_f32 v[18:19], v[30:31], v[28:29]
	v_and_b32_e32 v29, 0xffff0000, v16
	v_pk_mul_f32 v[18:19], v[26:27], v[18:19]
	v_lshlrev_b32_e32 v26, 16, v16
	v_mul_f32_e32 v15, 0xbfb8aa3b, v26
	v_exp_f32_e32 v16, v15
	v_mul_f32_e32 v15, 0xbfb8aa3b, v29
	v_exp_f32_e32 v27, v15
	v_cvt_pk_bf16_f32 v15, v18, v19
	v_add_f32_e32 v16, 1.0, v16
	v_rcp_f32_e32 v18, v16
	v_add_f32_e32 v16, 1.0, v27
	v_rcp_f32_e32 v19, v16
	v_and_b32_e32 v27, 0xffff0000, v20
	v_lshlrev_b32_e32 v28, 16, v20
	v_pk_mul_f32 v[26:27], v[28:29], v[26:27]
	v_and_b32_e32 v29, 0xffff0000, v17
	v_pk_mul_f32 v[18:19], v[18:19], v[26:27]
	v_lshlrev_b32_e32 v26, 16, v17
	v_mul_f32_e32 v16, 0xbfb8aa3b, v26
	v_exp_f32_e32 v17, v16
	v_mul_f32_e32 v16, 0xbfb8aa3b, v29
	v_exp_f32_e32 v20, v16
	v_cvt_pk_bf16_f32 v16, v18, v19
	v_add_f32_e32 v17, 1.0, v17
	v_rcp_f32_e32 v18, v17
	v_add_f32_e32 v17, 1.0, v20
	v_rcp_f32_e32 v19, v17
	v_and_b32_e32 v27, 0xffff0000, v21
	v_lshlrev_b32_e32 v28, 16, v21
	v_pk_mul_f32 v[20:21], v[28:29], v[26:27]
	v_and_b32_e32 v27, 0xffff0000, v8
	v_pk_mul_f32 v[18:19], v[18:19], v[20:21]
	v_lshlrev_b32_e32 v20, 16, v8
	v_mul_f32_e32 v8, 0xbfb8aa3b, v20
	v_exp_f32_e32 v8, v8
	v_mul_f32_e32 v21, 0xbfb8aa3b, v27
	v_exp_f32_e32 v21, v21
	v_cvt_pk_bf16_f32 v17, v18, v19
	v_lshl_add_u64 v[18:19], v[12:13], 0, v[204:205]
	v_add_f32_e32 v8, 1.0, v8
	global_store_dwordx4 v[18:19], v[14:17], off
	s_waitcnt lgkmcnt(0)
	v_lshlrev_b32_e32 v26, 16, v22
	v_and_b32_e32 v19, 0xffff0000, v9
	v_rcp_f32_e32 v14, v8
	v_add_f32_e32 v8, 1.0, v21
	v_rcp_f32_e32 v15, v8
	v_and_b32_e32 v21, 0xffff0000, v22
	v_pk_mul_f32 v[16:17], v[26:27], v[20:21]
	v_lshlrev_b32_e32 v18, 16, v23
	v_pk_mul_f32 v[14:15], v[14:15], v[16:17]
	v_lshlrev_b32_e32 v16, 16, v9
	v_mul_f32_e32 v8, 0xbfb8aa3b, v16
	v_exp_f32_e32 v9, v8
	v_mul_f32_e32 v8, 0xbfb8aa3b, v19
	v_exp_f32_e32 v17, v8
	v_cvt_pk_bf16_f32 v8, v14, v15
	v_add_f32_e32 v9, 1.0, v9
	v_rcp_f32_e32 v14, v9
	v_add_f32_e32 v9, 1.0, v17
	v_rcp_f32_e32 v15, v9
	v_and_b32_e32 v17, 0xffff0000, v23
	v_pk_mul_f32 v[16:17], v[18:19], v[16:17]
	v_and_b32_e32 v19, 0xffff0000, v10
	v_pk_mul_f32 v[14:15], v[14:15], v[16:17]
	v_lshlrev_b32_e32 v16, 16, v10
	v_mul_f32_e32 v9, 0xbfb8aa3b, v16
	v_exp_f32_e32 v10, v9
	v_mul_f32_e32 v9, 0xbfb8aa3b, v19
	v_exp_f32_e32 v17, v9
	v_cvt_pk_bf16_f32 v9, v14, v15
	v_add_f32_e32 v10, 1.0, v10
	v_rcp_f32_e32 v14, v10
	v_add_f32_e32 v10, 1.0, v17
	v_rcp_f32_e32 v15, v10
	v_and_b32_e32 v17, 0xffff0000, v24
	v_lshlrev_b32_e32 v18, 16, v24
	v_pk_mul_f32 v[16:17], v[18:19], v[16:17]
	v_and_b32_e32 v19, 0xffff0000, v11
	v_pk_mul_f32 v[14:15], v[14:15], v[16:17]
	v_lshlrev_b32_e32 v16, 16, v11
	v_mul_f32_e32 v10, 0xbfb8aa3b, v16
	v_exp_f32_e32 v11, v10
	v_mul_f32_e32 v10, 0xbfb8aa3b, v19
	v_exp_f32_e32 v17, v10
	v_cvt_pk_bf16_f32 v10, v14, v15
	v_add_f32_e32 v11, 1.0, v11
	v_rcp_f32_e32 v14, v11
	v_add_f32_e32 v11, 1.0, v17
	v_rcp_f32_e32 v15, v11
	v_and_b32_e32 v17, 0xffff0000, v25
	v_lshlrev_b32_e32 v18, 16, v25
	v_pk_mul_f32 v[16:17], v[18:19], v[16:17]
	v_lshlrev_b32_e32 v204, 11, v35
	v_pk_mul_f32 v[14:15], v[14:15], v[16:17]
	v_lshlrev_b32_e32 v18, 16, v4
	v_cvt_pk_bf16_f32 v11, v14, v15
	v_lshl_add_u64 v[14:15], v[12:13], 0, v[204:205]
	v_and_b32_e32 v21, 0xffff0000, v4
	v_mul_f32_e32 v4, 0xbfb8aa3b, v18
	global_store_dwordx4 v[14:15], v[8:11], off
	v_exp_f32_e32 v4, v4
	v_or_b32_e32 v24, 16, v32
	v_mul_f32_e32 v9, 0xbfb8aa3b, v21
	v_exp_f32_e32 v14, v9
	v_lshl_add_u32 v8, v24, 7, v34
	ds_read_b128 v[8:11], v8 offset:51200
	v_add_f32_e32 v4, 1.0, v4
	v_rcp_f32_e32 v22, v4
	v_add_f32_e32 v4, 1.0, v14
	v_rcp_f32_e32 v23, v4
	v_or_b32_e32 v25, 24, v32
	v_lshl_add_u32 v4, v25, 7, v34
	ds_read_b128 v[14:17], v4 offset:51200
	s_waitcnt lgkmcnt(1)
; __device__ __forceinline__ unsigned cvtpk_s(float lo,float hi){f32x2_t v={lo,hi};bf16x2_t b=__builtin_convertvector(v,bf16x2_t);return __builtin_bit_cast(unsigned,b);}
; template<int THRL> __device__ __forceinline__ void attn_unit(int b,int h,int qb,int t0,float cqv,float mfix,const float*__restrict__ cf,float cref,unsigned*counter,const bf16*Q,const bf16*__restrict__ K,const bf16*__restrict__ V,bf16*O,const bf16*__restrict__ G,char*shm){
;     ...
;     for(int i=0;i<4;++i){const int row=i*8+(lane>>3),ch=lane&7; const u32x4 v=*(const u32x4*)(stg+row*64+ch*8); const u32x4 gv=gv4[i]; u32x4 w;
;       #pragma unroll
;       for(int c=0;c<4;++c){ const float ol=__uint_as_float(v[c]<<16), oh=__uint_as_float(v[c]&0xffff0000u), gl=__uint_as_float(gv[c]<<16), gh=__uint_as_float(gv[c]&0xffff0000u);
;         const float rl=ol*gl*__builtin_amdgcn_rcpf(1.f+__expf(-gl)), rh=oh*gh*__builtin_amdgcn_rcpf(1.f+__expf(-gh)); w[c]=cvtpk_s(rl,rh); }
;       ATTN_STORE16(Ow+(long)row*DM+ch*8,w);} }
;   if(tid==0) *(volatile __attribute__((address_space(3))) int*)((__attribute__((address_space(3))) char*)shm+LDS_MISC)=unext_;
; template<int THRL> __device__ __forceinline__ void fox_attn_phase(char*lds,const bf16*Q,const bf16*K,const bf16*V,bf16*O,const bf16*G,const float*__restrict__ cumf,unsigned*counter,float TH,float mfix){
;     ...
;     { bool k0=true,k1=true;
;       if(lane<nb) k0=(cref-e0)>=-TH;
;       if(lane+64<nb) k1=(cref-e1)>=-TH;
;       const unsigned long long m0=__ballot(k0), m1=__ballot(k1);
;       int first=m0?__builtin_ctzll(m0):(m1?64+__builtin_ctzll(m1):128); if(first>nb)first=nb;
;       t0=__builtin_amdgcn_readfirstlane(first&~1); }
	v_and_b32_e32 v19, 0xffff0000, v8
	v_lshlrev_b32_e32 v20, 16, v8
	v_pk_mul_f32 v[18:19], v[20:21], v[18:19]
	v_lshlrev_b32_e32 v20, 16, v5
	v_pk_mul_f32 v[18:19], v[22:23], v[18:19]
	v_and_b32_e32 v23, 0xffff0000, v5
	v_mul_f32_e32 v4, 0xbfb8aa3b, v20
	v_exp_f32_e32 v5, v4
	v_mul_f32_e32 v4, 0xbfb8aa3b, v23
	v_exp_f32_e32 v8, v4
	v_cvt_pk_bf16_f32 v4, v18, v19
	v_add_f32_e32 v5, 1.0, v5
	v_rcp_f32_e32 v18, v5
	v_add_f32_e32 v5, 1.0, v8
	v_rcp_f32_e32 v19, v5
	v_and_b32_e32 v21, 0xffff0000, v9
	v_lshlrev_b32_e32 v22, 16, v9
	v_pk_mul_f32 v[8:9], v[22:23], v[20:21]
	v_and_b32_e32 v21, 0xffff0000, v6
	v_pk_mul_f32 v[8:9], v[18:19], v[8:9]
	v_lshlrev_b32_e32 v18, 16, v6
	v_mul_f32_e32 v5, 0xbfb8aa3b, v18
	v_exp_f32_e32 v6, v5
	v_mul_f32_e32 v5, 0xbfb8aa3b, v21
	v_exp_f32_e32 v19, v5
	v_cvt_pk_bf16_f32 v5, v8, v9
	v_add_f32_e32 v6, 1.0, v6
	v_rcp_f32_e32 v8, v6
	v_add_f32_e32 v6, 1.0, v19
	v_rcp_f32_e32 v9, v6
	v_and_b32_e32 v19, 0xffff0000, v10
	v_lshlrev_b32_e32 v20, 16, v10
	v_pk_mul_f32 v[18:19], v[20:21], v[18:19]
	v_and_b32_e32 v21, 0xffff0000, v7
	v_pk_mul_f32 v[8:9], v[8:9], v[18:19]
	v_lshlrev_b32_e32 v18, 16, v7
	v_mul_f32_e32 v6, 0xbfb8aa3b, v18
	v_exp_f32_e32 v7, v6
	v_mul_f32_e32 v6, 0xbfb8aa3b, v21
	v_exp_f32_e32 v10, v6
	v_cvt_pk_bf16_f32 v6, v8, v9
	v_add_f32_e32 v7, 1.0, v7
	v_rcp_f32_e32 v8, v7
	v_add_f32_e32 v7, 1.0, v10
	v_rcp_f32_e32 v9, v7
	v_and_b32_e32 v19, 0xffff0000, v11
	v_lshlrev_b32_e32 v20, 16, v11
	v_pk_mul_f32 v[10:11], v[20:21], v[18:19]
	v_and_b32_e32 v19, 0xffff0000, v0
	v_pk_mul_f32 v[8:9], v[8:9], v[10:11]
	v_lshlrev_b32_e32 v10, 16, v0
	v_mul_f32_e32 v0, 0xbfb8aa3b, v10
	v_exp_f32_e32 v0, v0
	v_mul_f32_e32 v11, 0xbfb8aa3b, v19
	v_exp_f32_e32 v11, v11
	v_lshlrev_b32_e32 v204, 11, v24
	v_cvt_pk_bf16_f32 v7, v8, v9
	v_lshl_add_u64 v[8:9], v[12:13], 0, v[204:205]
	v_add_f32_e32 v0, 1.0, v0
	global_store_dwordx4 v[8:9], v[4:7], off
	s_waitcnt lgkmcnt(0)
	v_lshlrev_b32_e32 v18, 16, v14
	v_and_b32_e32 v9, 0xffff0000, v1
	v_rcp_f32_e32 v4, v0
	v_add_f32_e32 v0, 1.0, v11
	v_rcp_f32_e32 v5, v0
	v_and_b32_e32 v11, 0xffff0000, v14
	v_pk_mul_f32 v[6:7], v[18:19], v[10:11]
	v_lshlrev_b32_e32 v8, 16, v15
	v_pk_mul_f32 v[4:5], v[4:5], v[6:7]
	v_lshlrev_b32_e32 v6, 16, v1
	v_mul_f32_e32 v0, 0xbfb8aa3b, v6
	v_exp_f32_e32 v1, v0
	v_mul_f32_e32 v0, 0xbfb8aa3b, v9
	v_exp_f32_e32 v7, v0
	v_cvt_pk_bf16_f32 v0, v4, v5
	v_add_f32_e32 v1, 1.0, v1
	v_rcp_f32_e32 v4, v1
	v_add_f32_e32 v1, 1.0, v7
	v_rcp_f32_e32 v5, v1
	v_and_b32_e32 v7, 0xffff0000, v15
	v_pk_mul_f32 v[6:7], v[8:9], v[6:7]
	v_and_b32_e32 v9, 0xffff0000, v2
	v_pk_mul_f32 v[4:5], v[4:5], v[6:7]
	v_lshlrev_b32_e32 v6, 16, v2
	v_mul_f32_e32 v1, 0xbfb8aa3b, v6
	v_exp_f32_e32 v2, v1
	v_mul_f32_e32 v1, 0xbfb8aa3b, v9
	v_exp_f32_e32 v7, v1
	v_cvt_pk_bf16_f32 v1, v4, v5
	v_add_f32_e32 v2, 1.0, v2
	v_rcp_f32_e32 v4, v2
	v_add_f32_e32 v2, 1.0, v7
	v_rcp_f32_e32 v5, v2
	v_and_b32_e32 v7, 0xffff0000, v16
	v_lshlrev_b32_e32 v8, 16, v16
	v_pk_mul_f32 v[6:7], v[8:9], v[6:7]
	v_and_b32_e32 v9, 0xffff0000, v3
	v_pk_mul_f32 v[4:5], v[4:5], v[6:7]
	v_lshlrev_b32_e32 v6, 16, v3
	v_mul_f32_e32 v2, 0xbfb8aa3b, v6
	v_exp_f32_e32 v3, v2
	v_mul_f32_e32 v2, 0xbfb8aa3b, v9
	v_exp_f32_e32 v7, v2
	v_cvt_pk_bf16_f32 v2, v4, v5
	v_add_f32_e32 v3, 1.0, v3
	v_rcp_f32_e32 v4, v3
	v_add_f32_e32 v3, 1.0, v7
	v_rcp_f32_e32 v5, v3
	v_and_b32_e32 v7, 0xffff0000, v17
	v_lshlrev_b32_e32 v8, 16, v17
	v_pk_mul_f32 v[6:7], v[8:9], v[6:7]
	v_lshlrev_b32_e32 v204, 11, v25
	v_pk_mul_f32 v[4:5], v[4:5], v[6:7]
	s_nop 0
	v_cvt_pk_bf16_f32 v3, v4, v5
	v_lshl_add_u64 v[4:5], v[12:13], 0, v[204:205]
	global_store_dwordx4 v[4:5], v[0:3], off
	v_readfirstlane_b32 s98, v216
	s_lshr_b32 s98, s98, 6
	s_cmp_lg_u32 s98, 0
	s_cbranch_scc1 .Lla2_skip
	v_readfirstlane_b32 s98, v252
	s_cmp_gt_u32 s98, 0x3ff
	s_cbranch_scc1 .Lla2_skip
	s_lshl_b32 s99, s99, 2
	s_waitcnt vmcnt(4)
	v_sub_f32_e32 v200, v199, v200
	v_sub_f32_e32 v201, v199, v201
	v_and_b32_e32 v197, 63, v216
	v_cmp_ge_f32_e64 s[100:101], v200, -v218
	s_nop 1
	v_cndmask_b32_e64 v200, 0, 1, s[100:101]
	v_cmp_le_u32_e64 s[100:101], s99, v197
	s_nop 1
	v_cndmask_b32_e64 v200, v200, 1, s[100:101]
	v_cmp_ne_u32_e64 s[100:101], 0, v200
	s_nop 3
	s_ff1_i32_b64 s98, s[100:101]
	s_cmp_lg_u64 s[100:101], 0
	s_cbranch_scc1 .Lla2_have
	v_add_u32_e32 v197, 64, v197
	v_cmp_ge_f32_e64 s[100:101], v201, -v218
	s_nop 1
	v_cndmask_b32_e64 v201, 0, 1, s[100:101]
	v_cmp_le_u32_e64 s[100:101], s99, v197
	s_nop 1
	v_cndmask_b32_e64 v201, v201, 1, s[100:101]
	v_cmp_ne_u32_e64 s[100:101], 0, v201
	s_nop 3
	s_ff1_i32_b64 s98, s[100:101]
	s_or_b32 s98, s98, 64
	s_cmp_lg_u64 s[100:101], 0
	s_cselect_b32 s98, s98, 0x80
.Lla2_have:
	v_mov_b32_e32 v196, s60
	v_mov_b32_e32 v198, s98
	ds_write_b32 v196, v198 offset:4
.Lla2_skip:
	s_and_saveexec_b64 s[4:5], vcc
	s_cbranch_execz .LBB0_844
	v_mov_b32_e32 v0, s60
	ds_write_b32 v0, v252
	s_branch .LBB0_844
